# seams P6-P8, P8-P9, P9-P10: per-XCD-class barrier (class-local data flow, no L2 writeback / cross-XCD hop) instead of the device-wide two-level barrier
# speedup vs baseline: 1.0160x; 1.0160x over previous
.LBB0_738:
	s_waitcnt vmcnt(0)
	s_barrier
	s_mov_b64 s[6:7], exec
	v_readlane_b32 s0, v254, 8
	v_readlane_b32 s1, v254, 9
	s_and_b64 s[0:1], s[6:7], s[0:1]
	s_mov_b64 exec, s[0:1]
	s_cbranch_execz .LBB0_790
	s_and_b32 s0, s74, 7
	s_lshl_b32 s0, s0, 8
	s_add_u32 s0, s0, 0x4000
	s_add_u32 s2, s92, s0
	s_addc_u32 s3, s93, 0
	v_mov_b32_e32 v0, 1
	s_waitcnt vmcnt(0) lgkmcnt(0)
	global_atomic_add v1, v197, v0, s[2:3] sc0
	buffer_inv sc1
	s_waitcnt vmcnt(0)
	v_readfirstlane_b32 s1, v1
	s_lshr_b32 s8, s1, 5
	s_and_b32 s1, s1, 31
	s_cmp_eq_u32 s1, 31
	s_cbranch_scc1 .Llb790_lead
	s_mov_b32 s9, 0
.Llb790_poll:
	global_load_dword v1, v197, s[2:3] offset:2048 sc1
	s_waitcnt vmcnt(0)
	v_readfirstlane_b32 s1, v1
	s_cmp_lg_u32 s1, s8
	s_cbranch_scc1 .Llb790_done
	s_sleep 1
	s_add_u32 s9, s9, 1
	s_cmp_lt_u32 s9, 0x40000
	s_cbranch_scc1 .Llb790_poll
	s_branch .Llb790_done
.Llb790_lead:
	global_atomic_add v197, v0, s[2:3] offset:2048
	s_waitcnt vmcnt(0)
.Llb790_done:
.LBB0_790:
	s_or_b64 exec, exec, s[6:7]
	s_waitcnt lgkmcnt(0)
	v_mov_b32_e32 v0, v211
	s_mov_b32 s0, s94
	s_mov_b32 s1, s74
	v_readlane_b32 s2, v255, 31
	s_mov_b64 s[6:7], s[92:93]
	v_mov_b32_e32 v14, v211
	s_barrier
	s_cmpk_gt_i32 s1, 0x57f
	v_readfirstlane_b32 s14, v14
	s_cbranch_scc1 .LBB0_806
	v_lshlrev_b32_e32 v0, 4, v14
	v_add_u32_e32 v1, 0x2000, v0
	v_ashrrev_i32_e32 v2, 31, v1
	v_lshrrev_b32_e32 v2, 22, v2
	v_add_u32_e32 v2, v1, v2
	v_ashrrev_i32_e32 v8, 10, v2
	v_mul_i32_i24_e32 v2, 0x400, v8
	v_sub_u32_e32 v1, v1, v2
	v_lshrrev_b32_e32 v2, 4, v1
	v_bitop3_b32 v1, v2, v1, 32 bitop3:0x6c
	v_ashrrev_i32_e32 v2, 31, v1
	v_lshrrev_b32_e32 v2, 26, v2
	v_add_u32_e32 v2, v1, v2
	v_lshlrev_b32_e32 v3, 3, v8
	v_ashrrev_i32_e32 v9, 6, v2
	v_and_b32_e32 v3, -16, v3
	v_add_u32_e32 v3, v9, v3
	v_and_b32_e32 v4, 3, v9
	s_mov_b32 s4, 0x1fffe0
	v_lshrrev_b32_e32 v5, 2, v3
	v_lshlrev_b32_e32 v6, 1, v3
	v_and_b32_e32 v2, 0xc0, v2
	v_and_or_b32 v4, v3, s4, v4
	v_and_b32_e32 v5, 4, v5
	v_and_b32_e32 v6, 24, v6
	v_sub_u32_e32 v1, v1, v2
	v_or3_b32 v4, v4, v5, v6
	v_lshlrev_b32_e32 v5, 5, v8
	v_ashrrev_i16_sdwa v1, v225, sext(v1) dst_sel:DWORD dst_unused:UNUSED_PAD src0_sel:DWORD src1_sel:BYTE_0
	v_and_b32_e32 v5, 32, v5
	v_bfe_i32 v10, v1, 0, 16
	v_add_lshl_u32 v1, v5, v10, 1
	v_lshl_add_u32 v128, v4, 11, v1
	v_lshl_add_u32 v130, v3, 11, v1
	v_bfe_i32 v1, v14, 27, 1
	v_lshrrev_b32_e32 v1, 22, v1
	v_add_u32_e32 v1, v0, v1
	v_and_b32_e32 v1, 0xfffffc00, v1
	v_sub_u32_e32 v0, v0, v1
	v_lshrrev_b32_e32 v1, 4, v0
	v_ashrrev_i32_e32 v2, 31, v14
	v_bitop3_b32 v0, v1, v0, 32 bitop3:0x6c
	v_lshrrev_b32_e32 v2, 26, v2
	v_ashrrev_i32_e32 v1, 31, v0
	v_add_u32_e32 v2, v14, v2
	s_add_u32 s2, s6, 0xae00000
	v_lshrrev_b32_e32 v1, 26, v1
	v_ashrrev_i32_e32 v12, 6, v2
	s_addc_u32 s3, s7, 0
	v_add_u32_e32 v1, v0, v1
	v_lshlrev_b32_e32 v2, 3, v12
	s_add_u32 s20, s6, 0xa10000
	v_ashrrev_i32_e32 v11, 6, v1
	v_and_b32_e32 v2, -16, v2
	s_addc_u32 s21, s7, 0
	v_add_u32_e32 v2, v11, v2
	v_and_b32_e32 v3, 3, v11
	s_ashr_i32 s23, s1, 31
	v_and_or_b32 v3, v2, s4, v3
	s_lshr_b32 s4, s23, 29
	s_add_i32 s4, s1, s4
	s_ashr_i32 s15, s14, 6
	s_ashr_i32 s8, s4, 3
	s_and_b32 s4, s4, -8
	s_ashr_i32 s16, s14, 8
	s_lshl_b32 s22, s15, 10
	s_sub_i32 s4, s1, s4
	s_cmp_lt_i32 s4, 0
	s_movk_i32 s9, 0xb1
	s_cselect_b32 s9, s9, 0xb0
	s_mul_i32 s4, s4, s9
	s_add_i32 s4, s4, s8
	s_mul_hi_i32 s8, s4, 0x2e8ba2e9
	s_lshr_b32 s9, s8, 31
	s_ashr_i32 s8, s8, 5
	s_add_i32 s8, s8, s9
	s_lshl_b32 s9, s8, 3
	s_mulk_i32 s8, 0xb0
	s_sub_i32 s8, s4, s8
	s_bfe_u32 s4, s8, 0x3001c
	s_add_i32 s12, s8, s4
	s_sext_i32_i16 s4, s12
	s_and_b32 s12, s12, 0xfff8
	s_sub_i32 s8, s8, s12
	s_sext_i32_i16 s8, s8
	v_lshrrev_b32_e32 v4, 2, v2
	v_lshlrev_b32_e32 v5, 1, v2
	v_and_b32_e32 v1, 0xc0, v1
	s_lshr_b32 s4, s4, 3
	s_add_i32 s44, s9, s8
	v_and_b32_e32 v4, 4, v4
	v_and_b32_e32 v5, 24, v5
	v_sub_u32_e32 v0, v0, v1
	s_ashr_i32 s45, s44, 31
	s_bfe_i64 s[12:13], s[4:5], 0x100000
	v_or3_b32 v3, v3, v4, v5
	v_lshlrev_b32_e32 v4, 5, v12
	v_ashrrev_i16_sdwa v0, v225, sext(v0) dst_sel:DWORD dst_unused:UNUSED_PAD src0_sel:DWORD src1_sel:BYTE_0
	s_lshl_b64 s[8:9], s[44:45], 19
	s_lshl_b64 s[12:13], s[12:13], 19
	v_and_b32_e32 v4, 32, v4
	v_bfe_i32 v13, v0, 0, 16
	s_add_u32 s48, s20, s12
	v_add_lshl_u32 v0, v4, v13, 1
	s_addc_u32 s49, s21, s13
	s_add_i32 s24, s22, 0
	v_lshl_add_u32 v196, v3, 11, v0
	s_add_i32 m0, s24, 0x10000
	v_lshl_add_u32 v132, v2, 11, v0
	global_load_lds_dwordx4 v196, s[48:49]
	s_add_i32 m0, s24, 0x12000
	s_add_u32 s12, s48, 0x40000
	global_load_lds_dwordx4 v128, s[48:49]
	s_addc_u32 s13, s49, 0
	s_add_i32 m0, s24, 0x14000
	v_mov_b32_e32 v129, v197
	global_load_lds_dwordx4 v196, s[12:13]
	s_add_i32 m0, s24, 0x16000
	s_add_u32 s46, s2, s8
	s_addc_u32 s47, s3, s9
	s_add_i32 s25, s24, 0x2000
	global_load_lds_dwordx4 v128, s[12:13]
	s_mov_b32 m0, s24
	s_add_u32 s8, s46, 0x40000
	global_load_lds_dwordx4 v132, s[46:47]
	s_mov_b32 m0, s25
	s_addc_u32 s9, s47, 0
	s_add_i32 s26, s24, 0x4000
	global_load_lds_dwordx4 v130, s[46:47]
	s_mov_b32 m0, s26
	s_add_i32 s27, s24, 0x6000
	global_load_lds_dwordx4 v132, s[8:9]
	s_mov_b32 m0, s27
	v_mov_b32_e32 v133, v197
	global_load_lds_dwordx4 v130, s[8:9]
	v_mov_b32_e32 v131, v197
	s_cmp_eq_u32 s16, 1
	v_lshl_add_u64 v[6:7], s[48:49], 0, v[196:197]
	v_lshl_add_u64 v[4:5], s[48:49], 0, v[128:129]
	v_lshl_add_u64 v[0:1], s[46:47], 0, v[132:133]
	s_cselect_b64 s[8:9], -1, 0
	s_cmp_lg_u32 s16, 1
	v_lshl_add_u64 v[2:3], s[46:47], 0, v[130:131]
	s_cbranch_scc1 .LBB0_793
	s_barrier

.LBB0_830:
	s_waitcnt vmcnt(0)
	s_waitcnt vmcnt(0)
	s_barrier
	s_mov_b64 s[6:7], exec
	v_readlane_b32 s0, v254, 8
	v_readlane_b32 s1, v254, 9
	s_and_b64 s[0:1], s[6:7], s[0:1]
	s_mov_b64 exec, s[0:1]
	s_cbranch_execz .LBB0_882
	s_and_b32 s0, s74, 7
	s_lshl_b32 s0, s0, 8
	s_add_u32 s0, s0, 0x4000
	s_add_u32 s2, s92, s0
	s_addc_u32 s3, s93, 0
	v_mov_b32_e32 v0, 1
	s_waitcnt vmcnt(0) lgkmcnt(0)
	global_atomic_add v1, v197, v0, s[2:3] sc0
	buffer_inv sc1
	s_waitcnt vmcnt(0)
	v_readfirstlane_b32 s1, v1
	s_lshr_b32 s8, s1, 5
	s_and_b32 s1, s1, 31
	s_cmp_eq_u32 s1, 31
	s_cbranch_scc1 .Llb882_lead
	s_mov_b32 s9, 0

.Llb882_done:
.LBB0_882:
	s_or_b64 exec, exec, s[6:7]
	s_waitcnt lgkmcnt(0)
	v_mov_b32_e32 v0, v211
	s_mov_b32 s0, s94
	s_mov_b32 s1, s74
	v_readlane_b32 s2, v255, 31
	s_mov_b64 s[8:9], s[92:93]
	v_mov_b32_e32 v8, v211
	s_barrier
	s_cmpk_lt_i32 s1, 0x100
	v_readfirstlane_b32 s12, v8
	s_cbranch_scc0 .LBB0_910
	s_ashr_i32 s2, s1, 31
	s_lshr_b32 s3, s2, 29
	s_add_i32 s4, s1, s3
	s_and_b32 s3, s4, -8
	s_sub_i32 s3, s1, s3
	s_cmp_gt_i32 s3, -1
	s_mov_b64 s[6:7], -1
	s_cbranch_scc0 .LBB0_885
	s_lshl_b32 s14, s3, 5
	s_mov_b64 s[6:7], 0

.Llb962_done:
.LBB0_962:
	s_or_b64 exec, exec, s[6:7]
	s_waitcnt lgkmcnt(0)
	v_mov_b32_e32 v0, v211
	s_mov_b32 s54, s94
	s_mov_b32 s55, s74
	v_readlane_b32 s0, v255, 31
	s_mov_b64 s[14:15], s[92:93]
	s_barrier
	s_add_u32 s16, s14, 0x1e00000
	s_addc_u32 s17, s15, 0
	s_add_u32 s56, s14, 0x1a90000
	s_addc_u32 s57, s15, 0
	s_mov_b32 s59, s0
	s_cmp_gt_i32 s0, 0
	s_mov_b64 s[6:7], -1
	s_cbranch_scc0 .LBB0_1017
	v_mov_b32_e32 v155, v211
	s_cmpk_gt_i32 s55, 0xff
	v_readfirstlane_b32 s58, v155
	s_cbranch_scc1 .LBB0_1016
	s_ashr_i32 s0, s55, 31
	s_lshr_b32 s1, s0, 29
	s_add_i32 s3, s55, s1
	s_and_b32 s1, s3, -8
	s_sub_i32 s1, s55, s1
	s_cmp_gt_i32 s1, -1
	s_cbranch_scc0 .LBB0_966
	s_lshl_b32 s2, s1, 5
	s_mov_b64 s[6:7], 0
